# merge split-K epilogue: 16 gate loads in flight, counted waits, 32-bit offsets
# speedup vs baseline: 1.1427x; 1.0046x over previous
; __device__ __forceinline__ f32x4 ld_bf4(const bf16_t* p) { const u32x2 w = *(const u32x2*)p; f32x4 r; r[0] = __uint_as_float(w.x << 16); r[1] = __uint_as_float(w.x & 0xffff0000u); r[2] = __uint_as_float(w.y << 16); r[3] = __uint_as_float(w.y & 0xffff0000u); return r; }
;     __device__ __forceinline__ void operator()(const f32x4 (&acc)[2][2][4][2], const Unit& u, int wr, int wc, int fr, int fq) const {
;         const int br = u.pm / 66, pmr = u.pm - br * 66 - 64, pn = u.pn & 3, slice = br * nks + (u.k0 >> 7);
; #pragma unroll
;         for (int ai = 0; ai < 2; ++ai)
; #pragma unroll
;             for (int m = 0; m < 4; ++m) { const int rs = pmr * 256 + ai * 128 + wr * 64 + m * 16 + fr;
; #pragma unroll
;                 for (int bj = 0; bj < 2; ++bj)
; #pragma unroll
;                     for (int n = 0; n < 2; ++n) { const int col = pn * 256 + bj * 128 + wc * 32 + 8 * fq + 4 * n; f32x4 v = acc[ai][bj][m][n];
;                         if (GT) v = v * ld_bf4(GT + (size_t)(cfg::MP + rs) * 3072 + br * 1024 + col);
;                         *(f32x4*)(P + ((size_t)slice * 512 + rs) * 1024 + col) = v; } }
.LBB0_444:
	s_mul_hi_i32 s13, s22, 0x3e0f83e1
	s_lshr_b32 s15, s13, 31
	s_ashr_i32 s13, s13, 4
	s_add_i32 s13, s13, s15
	s_mul_i32 s15, s13, 0xffffbe
	s_lshl_b32 s17, s13, 2
	s_ashr_i32 s21, s28, 7
	s_add_i32 s15, s15, s22
	s_add_i32 s22, s17, s21
	s_ashr_i32 s23, s22, 31
	v_lshl_add_u32 v138, s15, 8, v143
	s_lshl_b32 s15, s20, 8
	s_lshl_b64 s[20:21], s[22:23], 21
	s_lshl_b32 s22, s13, 10
	s_and_b32 s15, s15, 0x300
	s_ashr_i32 s23, s22, 31
	v_or_b32_e32 v156, s15, v144
	s_lshl_b64 s[22:23], s[22:23], 1
	s_add_u32 s20, s52, s20
	s_addc_u32 s21, s53, s21
	v_add_u32_e32 v139, 0x4000, v138
	v_lshlrev_b32_e32 v96, 1, v156
	v_mul_u32_u24_e32 v170, s61, v139
	v_add_u32_e32 v170, v170, v96
	v_add_u32_e32 v170, s22, v170
	v_lshlrev_b32_e32 v158, 12, v138
	v_lshl_add_u32 v158, v156, 2, v158
	v_add_u32_e32 v171, 0x18000, v170
	v_add_u32_e32 v159, 0x10000, v158
	v_add_u32_e32 v172, 0x30000, v170
	v_add_u32_e32 v160, 0x20000, v158
	v_add_u32_e32 v173, 0x48000, v170
	v_add_u32_e32 v161, 0x30000, v158
	v_add_u32_e32 v174, 0xc0000, v170
	v_add_u32_e32 v162, 0x80000, v158
	v_add_u32_e32 v175, 0xd8000, v170
	v_add_u32_e32 v163, 0x90000, v158
	v_add_u32_e32 v176, 0xf0000, v170
	v_add_u32_e32 v164, 0xa0000, v158
	v_add_u32_e32 v177, 0x108000, v170
	v_add_u32_e32 v165, 0xb0000, v158
	s_and_b64 vcc, exec, s[6:7]
	s_mov_b32 s72, 0xa00000
	s_mov_b32 s73, 0xc00000
	s_mov_b32 s70, 0x1200000
	s_mov_b32 s71, 0x1400000
	global_load_dwordx4 v[198:201], v170, s[2:3]
	global_load_dwordx4 v[202:205], v170, s[2:3] offset:256
	global_load_dwordx4 v[206:209], v171, s[2:3]
	global_load_dwordx4 v[210:213], v171, s[2:3] offset:256
	global_load_dwordx4 v[214:217], v172, s[2:3]
	global_load_dwordx4 v[218:221], v172, s[2:3] offset:256
	global_load_dwordx4 v[222:225], v173, s[2:3]
	global_load_dwordx4 v[226:229], v173, s[2:3] offset:256
	global_load_dwordx4 v[230:233], v174, s[2:3]
	global_load_dwordx4 v[234:237], v174, s[2:3] offset:256
	global_load_dwordx4 v[238:241], v175, s[2:3]
	global_load_dwordx4 v[242:245], v175, s[2:3] offset:256
	global_load_dwordx4 v[246:249], v176, s[2:3]
	global_load_dwordx4 v[250:253], v176, s[2:3] offset:256
	global_load_dwordx4 v[182:185], v177, s[2:3]
	global_load_dwordx4 v[186:189], v177, s[2:3] offset:256
	s_waitcnt vmcnt(14)
	v_lshlrev_b32_e32 v146, 16, v198
	v_and_b32_e32 v147, 0xffff0000, v198
	v_lshlrev_b32_e32 v148, 16, v199
	v_and_b32_e32 v149, 0xffff0000, v199
	v_pk_mul_f32 v[128:129], v[128:129], v[148:149]
	v_pk_mul_f32 v[126:127], v[126:127], v[146:147]
	v_lshlrev_b32_e32 v150, 16, v200
	v_and_b32_e32 v151, 0xffff0000, v200
	v_lshlrev_b32_e32 v152, 16, v201
	v_and_b32_e32 v153, 0xffff0000, v201
	v_pk_mul_f32 v[124:125], v[124:125], v[152:153]
	v_pk_mul_f32 v[122:123], v[122:123], v[150:151]
	v_lshlrev_b32_e32 v146, 16, v202
	v_and_b32_e32 v147, 0xffff0000, v202
	v_lshlrev_b32_e32 v148, 16, v203
	v_and_b32_e32 v149, 0xffff0000, v203
	v_pk_mul_f32 v[120:121], v[120:121], v[148:149]
	v_pk_mul_f32 v[118:119], v[118:119], v[146:147]
	v_lshlrev_b32_e32 v150, 16, v204
	v_and_b32_e32 v151, 0xffff0000, v204
	v_lshlrev_b32_e32 v152, 16, v205
	v_and_b32_e32 v153, 0xffff0000, v205
	v_pk_mul_f32 v[116:117], v[116:117], v[152:153]
	v_pk_mul_f32 v[114:115], v[114:115], v[150:151]
	global_store_dwordx4 v158, v[126:129], s[20:21]
	global_store_dwordx4 v158, v[122:125], s[20:21] offset:16
	global_store_dwordx4 v158, v[118:121], s[20:21] offset:512
	global_store_dwordx4 v158, v[114:117], s[20:21] offset:528
	s_waitcnt vmcnt(16)
	v_lshlrev_b32_e32 v146, 16, v206
	v_and_b32_e32 v147, 0xffff0000, v206
	v_lshlrev_b32_e32 v148, 16, v207
	v_and_b32_e32 v149, 0xffff0000, v207
	v_pk_mul_f32 v[112:113], v[112:113], v[148:149]
	v_pk_mul_f32 v[110:111], v[110:111], v[146:147]
	v_lshlrev_b32_e32 v150, 16, v208
	v_and_b32_e32 v151, 0xffff0000, v208
	v_lshlrev_b32_e32 v152, 16, v209
	v_and_b32_e32 v153, 0xffff0000, v209
	v_pk_mul_f32 v[108:109], v[108:109], v[152:153]
	v_pk_mul_f32 v[106:107], v[106:107], v[150:151]
	v_lshlrev_b32_e32 v146, 16, v210
	v_and_b32_e32 v147, 0xffff0000, v210
	v_lshlrev_b32_e32 v148, 16, v211
	v_and_b32_e32 v149, 0xffff0000, v211
	v_pk_mul_f32 v[104:105], v[104:105], v[148:149]
	v_pk_mul_f32 v[102:103], v[102:103], v[146:147]
	v_lshlrev_b32_e32 v150, 16, v212
	v_and_b32_e32 v151, 0xffff0000, v212
	v_lshlrev_b32_e32 v152, 16, v213
	v_and_b32_e32 v153, 0xffff0000, v213
	v_pk_mul_f32 v[100:101], v[100:101], v[152:153]
	v_pk_mul_f32 v[98:99], v[98:99], v[150:151]
	global_store_dwordx4 v159, v[110:113], s[20:21]
	global_store_dwordx4 v159, v[106:109], s[20:21] offset:16
	global_store_dwordx4 v159, v[102:105], s[20:21] offset:512
	global_store_dwordx4 v159, v[98:101], s[20:21] offset:528
	s_waitcnt vmcnt(18)
	v_lshlrev_b32_e32 v146, 16, v214
	v_and_b32_e32 v147, 0xffff0000, v214
	v_lshlrev_b32_e32 v148, 16, v215
	v_and_b32_e32 v149, 0xffff0000, v215
	v_pk_mul_f32 v[94:95], v[94:95], v[148:149]
	v_pk_mul_f32 v[92:93], v[92:93], v[146:147]
	v_lshlrev_b32_e32 v150, 16, v216
	v_and_b32_e32 v151, 0xffff0000, v216
	v_lshlrev_b32_e32 v152, 16, v217
	v_and_b32_e32 v153, 0xffff0000, v217
	v_pk_mul_f32 v[90:91], v[90:91], v[152:153]
	v_pk_mul_f32 v[88:89], v[88:89], v[150:151]
	v_lshlrev_b32_e32 v146, 16, v218
	v_and_b32_e32 v147, 0xffff0000, v218
	v_lshlrev_b32_e32 v148, 16, v219
	v_and_b32_e32 v149, 0xffff0000, v219
	v_pk_mul_f32 v[86:87], v[86:87], v[148:149]
	v_pk_mul_f32 v[84:85], v[84:85], v[146:147]
	v_lshlrev_b32_e32 v150, 16, v220
	v_and_b32_e32 v151, 0xffff0000, v220
	v_lshlrev_b32_e32 v152, 16, v221
	v_and_b32_e32 v153, 0xffff0000, v221
	v_pk_mul_f32 v[82:83], v[82:83], v[152:153]
	v_pk_mul_f32 v[80:81], v[80:81], v[150:151]
	global_store_dwordx4 v160, v[92:95], s[20:21]
	global_store_dwordx4 v160, v[88:91], s[20:21] offset:16
	global_store_dwordx4 v160, v[84:87], s[20:21] offset:512
	global_store_dwordx4 v160, v[80:83], s[20:21] offset:528
	s_waitcnt vmcnt(20)
; __device__ __forceinline__ f32x4 ld_bf4(const bf16_t* p) { const u32x2 w = *(const u32x2*)p; f32x4 r; r[0] = __uint_as_float(w.x << 16); r[1] = __uint_as_float(w.x & 0xffff0000u); r[2] = __uint_as_float(w.y << 16); r[3] = __uint_as_float(w.y & 0xffff0000u); return r; }
;     __device__ __forceinline__ void operator()(const f32x4 (&acc)[2][2][4][2], const Unit& u, int wr, int wc, int fr, int fq) const {
;     ...
;         for (int ai = 0; ai < 2; ++ai)
; #pragma unroll
;             for (int m = 0; m < 4; ++m) { const int rs = pmr * 256 + ai * 128 + wr * 64 + m * 16 + fr;
; #pragma unroll
;                 for (int bj = 0; bj < 2; ++bj)
; #pragma unroll
;                     for (int n = 0; n < 2; ++n) { const int col = pn * 256 + bj * 128 + wc * 32 + 8 * fq + 4 * n; f32x4 v = acc[ai][bj][m][n];
;                         if (GT) v = v * ld_bf4(GT + (size_t)(cfg::MP + rs) * 3072 + br * 1024 + col);
;                         *(f32x4*)(P + ((size_t)slice * 512 + rs) * 1024 + col) = v; } }
	v_lshlrev_b32_e32 v146, 16, v222
	v_and_b32_e32 v147, 0xffff0000, v222
	v_lshlrev_b32_e32 v148, 16, v223
	v_and_b32_e32 v149, 0xffff0000, v223
	v_pk_mul_f32 v[78:79], v[78:79], v[148:149]
	v_pk_mul_f32 v[76:77], v[76:77], v[146:147]
	v_lshlrev_b32_e32 v150, 16, v224
	v_and_b32_e32 v151, 0xffff0000, v224
	v_lshlrev_b32_e32 v152, 16, v225
	v_and_b32_e32 v153, 0xffff0000, v225
	v_pk_mul_f32 v[74:75], v[74:75], v[152:153]
	v_pk_mul_f32 v[72:73], v[72:73], v[150:151]
	v_lshlrev_b32_e32 v146, 16, v226
	v_and_b32_e32 v147, 0xffff0000, v226
	v_lshlrev_b32_e32 v148, 16, v227
	v_and_b32_e32 v149, 0xffff0000, v227
	v_pk_mul_f32 v[70:71], v[70:71], v[148:149]
	v_pk_mul_f32 v[68:69], v[68:69], v[146:147]
	v_lshlrev_b32_e32 v150, 16, v228
	v_and_b32_e32 v151, 0xffff0000, v228
	v_lshlrev_b32_e32 v152, 16, v229
	v_and_b32_e32 v153, 0xffff0000, v229
	v_pk_mul_f32 v[66:67], v[66:67], v[152:153]
	v_pk_mul_f32 v[64:65], v[64:65], v[150:151]
	global_store_dwordx4 v161, v[76:79], s[20:21]
	global_store_dwordx4 v161, v[72:75], s[20:21] offset:16
	global_store_dwordx4 v161, v[68:71], s[20:21] offset:512
	global_store_dwordx4 v161, v[64:67], s[20:21] offset:528
	s_waitcnt vmcnt(22)
	v_lshlrev_b32_e32 v146, 16, v230
	v_and_b32_e32 v147, 0xffff0000, v230
	v_lshlrev_b32_e32 v148, 16, v231
	v_and_b32_e32 v149, 0xffff0000, v231
	v_pk_mul_f32 v[62:63], v[62:63], v[148:149]
	v_pk_mul_f32 v[60:61], v[60:61], v[146:147]
	v_lshlrev_b32_e32 v150, 16, v232
	v_and_b32_e32 v151, 0xffff0000, v232
	v_lshlrev_b32_e32 v152, 16, v233
	v_and_b32_e32 v153, 0xffff0000, v233
	v_pk_mul_f32 v[58:59], v[58:59], v[152:153]
	v_pk_mul_f32 v[56:57], v[56:57], v[150:151]
	v_lshlrev_b32_e32 v146, 16, v234
	v_and_b32_e32 v147, 0xffff0000, v234
	v_lshlrev_b32_e32 v148, 16, v235
	v_and_b32_e32 v149, 0xffff0000, v235
	v_pk_mul_f32 v[54:55], v[54:55], v[148:149]
	v_pk_mul_f32 v[52:53], v[52:53], v[146:147]
	v_lshlrev_b32_e32 v150, 16, v236
	v_and_b32_e32 v151, 0xffff0000, v236
	v_lshlrev_b32_e32 v152, 16, v237
	v_and_b32_e32 v153, 0xffff0000, v237
	v_pk_mul_f32 v[50:51], v[50:51], v[152:153]
	v_pk_mul_f32 v[48:49], v[48:49], v[150:151]
	global_store_dwordx4 v162, v[60:63], s[20:21]
	global_store_dwordx4 v162, v[56:59], s[20:21] offset:16
	global_store_dwordx4 v162, v[52:55], s[20:21] offset:512
	global_store_dwordx4 v162, v[48:51], s[20:21] offset:528
	s_waitcnt vmcnt(24)
	v_lshlrev_b32_e32 v146, 16, v238
	v_and_b32_e32 v147, 0xffff0000, v238
	v_lshlrev_b32_e32 v148, 16, v239
	v_and_b32_e32 v149, 0xffff0000, v239
	v_pk_mul_f32 v[46:47], v[46:47], v[148:149]
	v_pk_mul_f32 v[44:45], v[44:45], v[146:147]
	v_lshlrev_b32_e32 v150, 16, v240
	v_and_b32_e32 v151, 0xffff0000, v240
	v_lshlrev_b32_e32 v152, 16, v241
	v_and_b32_e32 v153, 0xffff0000, v241
	v_pk_mul_f32 v[42:43], v[42:43], v[152:153]
	v_pk_mul_f32 v[40:41], v[40:41], v[150:151]
	v_lshlrev_b32_e32 v146, 16, v242
	v_and_b32_e32 v147, 0xffff0000, v242
	v_lshlrev_b32_e32 v148, 16, v243
	v_and_b32_e32 v149, 0xffff0000, v243
	v_pk_mul_f32 v[38:39], v[38:39], v[148:149]
	v_pk_mul_f32 v[36:37], v[36:37], v[146:147]
	v_lshlrev_b32_e32 v150, 16, v244
	v_and_b32_e32 v151, 0xffff0000, v244
	v_lshlrev_b32_e32 v152, 16, v245
	v_and_b32_e32 v153, 0xffff0000, v245
	v_pk_mul_f32 v[34:35], v[34:35], v[152:153]
	v_pk_mul_f32 v[32:33], v[32:33], v[150:151]
	global_store_dwordx4 v163, v[44:47], s[20:21]
	global_store_dwordx4 v163, v[40:43], s[20:21] offset:16
	global_store_dwordx4 v163, v[36:39], s[20:21] offset:512
	global_store_dwordx4 v163, v[32:35], s[20:21] offset:528
	s_waitcnt vmcnt(26)
	v_lshlrev_b32_e32 v146, 16, v246
	v_and_b32_e32 v147, 0xffff0000, v246
	v_lshlrev_b32_e32 v148, 16, v247
	v_and_b32_e32 v149, 0xffff0000, v247
	v_pk_mul_f32 v[30:31], v[30:31], v[148:149]
	v_pk_mul_f32 v[28:29], v[28:29], v[146:147]
	v_lshlrev_b32_e32 v150, 16, v248
	v_and_b32_e32 v151, 0xffff0000, v248
	v_lshlrev_b32_e32 v152, 16, v249
	v_and_b32_e32 v153, 0xffff0000, v249
	v_pk_mul_f32 v[26:27], v[26:27], v[152:153]
	v_pk_mul_f32 v[24:25], v[24:25], v[150:151]
	v_lshlrev_b32_e32 v146, 16, v250
	v_and_b32_e32 v147, 0xffff0000, v250
	v_lshlrev_b32_e32 v148, 16, v251
	v_and_b32_e32 v149, 0xffff0000, v251
	v_pk_mul_f32 v[22:23], v[22:23], v[148:149]
	v_pk_mul_f32 v[20:21], v[20:21], v[146:147]
	v_lshlrev_b32_e32 v150, 16, v252
	v_and_b32_e32 v151, 0xffff0000, v252
	v_lshlrev_b32_e32 v152, 16, v253
	v_and_b32_e32 v153, 0xffff0000, v253
	v_pk_mul_f32 v[18:19], v[18:19], v[152:153]
	v_pk_mul_f32 v[16:17], v[16:17], v[150:151]
	global_store_dwordx4 v164, v[28:31], s[20:21]
	global_store_dwordx4 v164, v[24:27], s[20:21] offset:16
	global_store_dwordx4 v164, v[20:23], s[20:21] offset:512
	global_store_dwordx4 v164, v[16:19], s[20:21] offset:528
	s_waitcnt vmcnt(28)
	v_lshlrev_b32_e32 v146, 16, v182
	v_and_b32_e32 v147, 0xffff0000, v182
	v_lshlrev_b32_e32 v148, 16, v183
	v_and_b32_e32 v149, 0xffff0000, v183
	v_pk_mul_f32 v[14:15], v[14:15], v[148:149]
	v_pk_mul_f32 v[12:13], v[12:13], v[146:147]
	v_lshlrev_b32_e32 v150, 16, v184
	v_and_b32_e32 v151, 0xffff0000, v184
	v_lshlrev_b32_e32 v152, 16, v185
	v_and_b32_e32 v153, 0xffff0000, v185
	v_pk_mul_f32 v[10:11], v[10:11], v[152:153]
	v_pk_mul_f32 v[8:9], v[8:9], v[150:151]
	v_lshlrev_b32_e32 v146, 16, v186
	v_and_b32_e32 v147, 0xffff0000, v186
	v_lshlrev_b32_e32 v148, 16, v187
	v_and_b32_e32 v149, 0xffff0000, v187
	v_pk_mul_f32 v[6:7], v[6:7], v[148:149]
	v_pk_mul_f32 v[4:5], v[4:5], v[146:147]
	v_lshlrev_b32_e32 v150, 16, v188
	v_and_b32_e32 v151, 0xffff0000, v188
	v_lshlrev_b32_e32 v152, 16, v189
	v_and_b32_e32 v153, 0xffff0000, v189
	v_pk_mul_f32 v[2:3], v[2:3], v[152:153]
	v_pk_mul_f32 v[0:1], v[0:1], v[150:151]
	global_store_dwordx4 v165, v[12:15], s[20:21]
	global_store_dwordx4 v165, v[8:11], s[20:21] offset:16
	global_store_dwordx4 v165, v[4:7], s[20:21] offset:512
	global_store_dwordx4 v165, v[0:3], s[20:21] offset:528
	s_nop 0
	s_mov_b64 s[20:21], -1
	s_cbranch_vccnz .LBB0_435
	s_andn2_b64 vcc, exec, s[8:9]
	s_cbranch_vccnz .LBB0_434
	s_barrier
	s_branch .LBB0_434
